# rowpost per-row loads prefetched at loop top (2 round trips/row instead of 12), K-path nope epilogue: 32 serialized bpermute hops batched into 2 rounds
# speedup vs baseline: 1.0050x; 1.0050x over previous
.LBB0_536:
	v_mov_b64_e32 v[34:35], s[12:13]
	s_movk_i32 s0, 0x2800
	v_mad_i64_i32 v[36:37], s[0:1], v4, s0, v[34:35]
	v_mov_b32_e32 v31, v1
	v_lshl_add_u64 v[34:35], v[36:37], 0, v[30:31]
	global_load_dword v0, v[34:35], off
	global_load_dwordx2 v[42:43], v[22:23], off
	global_load_dword v101, v[34:35], off offset:256
	global_load_dword v102, v[34:35], off offset:512
	v_lshlrev_b32_e32 v108, 1, v8
	v_mov_b32_e32 v109, v1
	v_lshl_add_u64 v[108:109], v[36:37], 0, v[108:109]
	global_load_dwordx4 v[104:107], v[108:109], off offset:768
	global_load_dwordx4 v[112:115], v[108:109], off offset:3968
	s_mov_b64 s[16:17], 0xf80
	v_lshl_add_u64 v[136:137], v[108:109], 0, s[16:17]
	global_load_dwordx4 v[116:119], v[136:137], off offset:1024
	v_mov_b32_e32 v110, v32
	v_mov_b32_e32 v111, v1
	v_lshl_add_u64 v[110:111], v[36:37], 0, v[110:111]
	global_load_ushort v103, v[110:111], off offset:1792
	global_load_dwordx2 v[122:123], v[22:23], off offset:512
	global_load_dwordx2 v[124:125], v[22:23], off offset:1024
	global_load_dwordx4 v[126:129], v[10:11], off offset:16
	global_load_dwordx4 v[130:133], v[10:11], off
	global_load_dword v134, v[14:15], off
	s_movk_i32 s0, 0x3fff
	v_cmp_lt_i32_e64 s[8:9], s0, v4
	s_movk_i32 s0, 0x300
	v_mad_i64_i32 v[44:45], s[0:1], v4, s0, v[26:27]
	s_mov_b32 s0, 0x800000
	v_ashrrev_i32_e32 v5, 31, v4
	v_mov_b32_e32 v33, v1
	s_waitcnt vmcnt(0)
	v_lshlrev_b32_e32 v38, 16, v0
	v_and_b32_e32 v39, 0xffff0000, v0
	v_mov_b32_e32 v0, v101
	v_mov_b32_e32 v56, v39
	v_mov_b32_e32 v48, v38
	v_lshlrev_b32_e32 v40, 16, v0
	v_and_b32_e32 v41, 0xffff0000, v0
	v_mov_b32_e32 v0, v102
	v_pk_mul_f32 v[46:47], v[40:41], v[40:41]
	v_and_b32_e32 v35, 0xffff0000, v0
	v_lshlrev_b32_e32 v34, 16, v0
	v_mov_b32_e32 v57, v35
	v_mov_b32_e32 v49, v34
	v_pk_mul_f32 v[56:57], v[56:57], v[56:57]
	v_add_f32_e32 v0, v46, v47
	v_pk_fma_f32 v[48:49], v[48:49], v[48:49], v[56:57]
	s_nop 0
	v_add_f32_e32 v0, v48, v0
	v_add_f32_e32 v0, v0, v49
	ds_bpermute_b32 v9, v3, v0
	s_waitcnt lgkmcnt(0)
	v_add_f32_e32 v0, v0, v9
	ds_bpermute_b32 v9, v7, v0
	s_waitcnt lgkmcnt(0)
	v_add_f32_e32 v0, v0, v9
	ds_bpermute_b32 v9, v51, v0
	s_waitcnt lgkmcnt(0)
	v_add_f32_e32 v0, v0, v9
	ds_bpermute_b32 v9, v52, v0
	s_waitcnt lgkmcnt(0)
	v_add_f32_e32 v0, v0, v9
	ds_bpermute_b32 v9, v53, v0
	s_waitcnt lgkmcnt(0)
	v_add_f32_e32 v0, v0, v9
	ds_bpermute_b32 v9, v54, v0
	s_waitcnt lgkmcnt(0)
	v_add_f32_e32 v0, v0, v9
	v_fmamk_f32 v0, v0, 0x3b2aaaab, v167
	v_cmp_gt_f32_e32 vcc, s0, v0
	v_mul_f32_e32 v9, 0x4b800000, v0
	s_nop 0
	v_cndmask_b32_e32 v0, v0, v9, vcc
	v_rsq_f32_e32 v0, v0
	s_nop 0
	v_mul_f32_e32 v9, 0x45800000, v0
	v_cndmask_b32_e32 v0, v0, v9, vcc
	v_pk_mul_f32 v[38:39], v[0:1], v[38:39] op_sel_hi:[0,1]
	v_pk_mul_f32 v[38:39], v[42:43], v[38:39]
	v_pk_mul_f32 v[40:41], v[0:1], v[40:41] op_sel_hi:[0,1]
	v_cvt_pk_bf16_f32 v9, v38, v39
	global_store_dword v[44:45], v9, off
	v_mov_b64_e32 v[38:39], v[122:123]
	v_pk_mul_f32 v[34:35], v[0:1], v[34:35] op_sel_hi:[0,1]
	v_pk_mul_f32 v[38:39], v[38:39], v[40:41]
	s_nop 0
	v_cvt_pk_bf16_f32 v9, v38, v39
	global_store_dword v[44:45], v9, off offset:256
	v_mov_b64_e32 v[38:39], v[124:125]
	v_pk_mul_f32 v[34:35], v[38:39], v[34:35]
	s_nop 0
	v_cvt_pk_bf16_f32 v0, v34, v35
	global_store_dword v[44:45], v0, off offset:512
	v_lshlrev_b32_e32 v0, 1, v8
	v_lshl_add_u64 v[34:35], v[36:37], 0, v[0:1]
	v_mov_b64_e32 v[38:39], v[104:105]
	v_mov_b64_e32 v[40:41], v[106:107]
	v_add_u32_e32 v0, 0xffffc000, v4
	v_lshl_add_u64 v[36:37], v[36:37], 0, v[32:33]
	v_lshlrev_b32_e32 v46, 16, v38
	v_and_b32_e32 v47, 0xffff0000, v38
	v_lshlrev_b32_e32 v48, 16, v39
	v_and_b32_e32 v49, 0xffff0000, v39
	v_lshlrev_b32_e32 v56, 16, v40
	v_and_b32_e32 v57, 0xffff0000, v40
	v_lshlrev_b32_e32 v58, 16, v41
	v_and_b32_e32 v59, 0xffff0000, v41
	v_lshlrev_b64 v[38:39], 11, v[0:1]
	v_lshlrev_b64 v[40:41], 11, v[4:5]
	v_lshl_add_u64 v[38:39], s[36:37], 0, v[38:39]
	v_lshl_add_u64 v[40:41], s[30:31], 0, v[40:41]
	v_cndmask_b32_e64 v39, v41, v39, s[8:9]
	v_cndmask_b32_e64 v38, v40, v38, s[8:9]
	v_lshlrev_b32_e32 v40, 2, v8
	v_mov_b32_e32 v41, v1
	v_lshl_add_u64 v[60:61], v[38:39], 0, v[40:41]
	v_mov_b64_e32 v[38:39], v[126:127]
	v_mov_b64_e32 v[40:41], v[128:129]
	v_mov_b64_e32 v[42:43], v[130:131]
	v_mov_b64_e32 v[44:45], v[132:133]
	v_pk_mul_f32 v[62:63], v[46:47], v[46:47]
	v_pk_mul_f32 v[64:65], v[48:49], v[48:49]
	v_add_f32_e32 v9, v62, v63
	v_add_f32_e32 v9, v9, v64
	v_pk_mul_f32 v[66:67], v[56:57], v[56:57]
	v_add_f32_e32 v9, v65, v9
	v_add_f32_e32 v9, v66, v9
	v_pk_mul_f32 v[68:69], v[58:59], v[58:59]
	v_add_f32_e32 v9, v67, v9
	v_add_f32_e32 v9, v68, v9
	v_add_f32_e32 v9, v69, v9
	ds_bpermute_b32 v31, v3, v9
	s_waitcnt lgkmcnt(0)
	v_add_f32_e32 v9, v9, v31
	ds_bpermute_b32 v31, v7, v9
	s_waitcnt lgkmcnt(0)
	v_add_f32_e32 v9, v9, v31
	ds_bpermute_b32 v31, v51, v9
	s_waitcnt lgkmcnt(0)
	v_add_f32_e32 v9, v9, v31
	ds_bpermute_b32 v31, v52, v9
	s_waitcnt lgkmcnt(0)
	v_add_f32_e32 v9, v9, v31
	ds_bpermute_b32 v31, v53, v9
	s_waitcnt lgkmcnt(0)
	v_add_f32_e32 v9, v9, v31
	ds_bpermute_b32 v31, v54, v9
	s_waitcnt lgkmcnt(0)
	v_add_f32_e32 v9, v9, v31
	v_fmamk_f32 v9, v9, 0x3b000000, v167
	v_cmp_gt_f32_e32 vcc, s0, v9
	v_mul_f32_e32 v31, 0x4b800000, v9
	s_nop 0
	v_cndmask_b32_e32 v9, v9, v31, vcc
	v_rsq_f32_e32 v9, v9
	s_nop 0
	v_mul_f32_e32 v31, 0x45800000, v9
	v_cndmask_b32_e32 v50, v9, v31, vcc
	v_pk_mul_f32 v[46:47], v[50:51], v[46:47] op_sel_hi:[0,1]
	v_pk_mul_f32 v[42:43], v[42:43], v[46:47]
	v_pk_mul_f32 v[46:47], v[50:51], v[48:49] op_sel_hi:[0,1]
	v_pk_mul_f32 v[44:45], v[44:45], v[46:47]
	v_pk_mul_f32 v[46:47], v[50:51], v[56:57] op_sel_hi:[0,1]
	v_pk_mul_f32 v[38:39], v[38:39], v[46:47]
	v_pk_mul_f32 v[46:47], v[50:51], v[58:59] op_sel_hi:[0,1]
	v_pk_mul_f32 v[40:41], v[40:41], v[46:47]
	global_store_dwordx4 v[60:61], v[42:45], off
	global_store_dwordx4 v[60:61], v[38:41], off offset:16
	s_nop 0
	v_cvt_pk_bf16_f32 v42, v42, v43
	v_cvt_pk_bf16_f32 v43, v44, v45
	v_cvt_pk_bf16_f32 v44, v38, v39
	v_lshlrev_b64 v[38:39], 10, v[4:5]
	v_cvt_pk_bf16_f32 v45, v40, v41
	v_lshl_add_u64 v[38:39], v[12:13], 0, v[38:39]
	global_store_dwordx4 v[38:39], v[42:45], off
	v_mov_b32_e32 v9, v103
	v_lshlrev_b32_e32 v9, 16, v9
	v_mul_f32_e32 v31, v9, v9
	ds_bpermute_b32 v31, v3, v31
	s_waitcnt lgkmcnt(0)
	v_fmac_f32_e32 v31, v9, v9
	ds_bpermute_b32 v33, v7, v31
	s_waitcnt lgkmcnt(0)
	v_add_f32_e32 v31, v31, v33
	ds_bpermute_b32 v33, v51, v31
	s_waitcnt lgkmcnt(0)
	v_add_f32_e32 v31, v31, v33
	ds_bpermute_b32 v33, v52, v31
	s_waitcnt lgkmcnt(0)
	v_add_f32_e32 v31, v31, v33
	ds_bpermute_b32 v33, v53, v31
	s_waitcnt lgkmcnt(0)
	v_add_f32_e32 v31, v31, v33
	ds_bpermute_b32 v33, v54, v31
	s_waitcnt lgkmcnt(0)
	v_add_f32_e32 v31, v31, v33
	v_fmamk_f32 v31, v31, 0x3c800000, v167
	v_cmp_gt_f32_e32 vcc, s0, v31
	v_mul_f32_e32 v33, 0x4b800000, v31
	s_movk_i32 s0, 0x4000
	v_cndmask_b32_e32 v31, v31, v33, vcc
	v_rsq_f32_e32 v31, v31
	s_nop 0
	v_mul_f32_e32 v33, 0x45800000, v31
	v_cndmask_b32_e32 v31, v31, v33, vcc
	v_mul_f32_e32 v9, v31, v9
	v_mov_b32_e32 v31, v134
	v_cmp_gt_i32_e32 vcc, s0, v4
	v_mul_f32_e32 v33, v31, v9
	v_and_b32_e32 v9, 15, v4
	v_or_b32_e32 v36, 0x1000, v9
	v_cndmask_b32_e32 v36, v36, v4, vcc
	v_ashrrev_i32_e32 v37, 31, v36
	v_lshlrev_b64 v[36:37], 8, v[36:37]
	v_lshl_add_u64 v[36:37], v[16:17], 0, v[36:37]
	global_load_dwordx2 v[36:37], v[36:37], off
	ds_bpermute_b32 v31, v3, v33
	s_waitcnt vmcnt(0) lgkmcnt(0)
	v_mul_f32_e32 v31, v37, v31
	v_cndmask_b32_e64 v31, v31, -v31, s[4:5]
	v_fmac_f32_e32 v31, v36, v33
	s_and_saveexec_b64 s[0:1], vcc
	s_xor_b64 s[16:17], exec, s[0:1]
	s_cbranch_execz .LBB0_538
	v_lshlrev_b64 v[36:37], 6, v[4:5]
	v_or_b32_e32 v36, v36, v6
	v_lshl_add_u64 v[38:39], v[36:37], 2, s[34:35]
	v_cvt_pk_bf16_f32 v9, v31, s0
	v_lshl_add_u64 v[36:37], v[36:37], 1, s[18:19]
	global_store_dword v[38:39], v31, off
	global_store_short v[36:37], v9, off

.LBB0_540:
	s_or_b64 exec, exec, s[16:17]
	v_mov_b64_e32 v[36:37], v[112:113]
	v_mov_b64_e32 v[38:39], v[114:115]
	s_mov_b64 s[0:1], 0xf80
	v_lshl_add_u64 v[34:35], v[34:35], 0, s[0:1]
	v_mov_b64_e32 v[56:57], v[116:117]
	v_mov_b64_e32 v[58:59], v[118:119]
	s_mov_b32 s0, 0x800000
	v_lshlrev_b32_e32 v46, 16, v36
	v_and_b32_e32 v47, 0xffff0000, v36
	v_lshlrev_b32_e32 v48, 16, v37
	v_and_b32_e32 v49, 0xffff0000, v37
	v_pk_mul_f32 v[60:61], v[46:47], v[46:47]
	v_pk_mul_f32 v[62:63], v[48:49], v[48:49]
	v_add_f32_e32 v9, v60, v61
	v_lshlrev_b32_e32 v42, 16, v38
	v_and_b32_e32 v43, 0xffff0000, v38
	v_add_f32_e32 v9, v9, v62
	v_pk_mul_f32 v[64:65], v[42:43], v[42:43]
	v_add_f32_e32 v9, v63, v9
	v_lshlrev_b32_e32 v44, 16, v39
	v_and_b32_e32 v45, 0xffff0000, v39
	v_add_f32_e32 v9, v64, v9
	v_pk_mul_f32 v[66:67], v[44:45], v[44:45]
	v_add_f32_e32 v9, v65, v9
	v_lshlrev_b32_e32 v38, 16, v56
	v_and_b32_e32 v39, 0xffff0000, v56
	v_add_f32_e32 v9, v66, v9
	v_lshlrev_b32_e32 v40, 16, v57
	v_and_b32_e32 v41, 0xffff0000, v57
	v_pk_mul_f32 v[56:57], v[38:39], v[38:39]
	v_add_f32_e32 v9, v67, v9
	v_add_f32_e32 v9, v56, v9
	v_lshlrev_b32_e32 v34, 16, v58
	v_and_b32_e32 v35, 0xffff0000, v58
	v_lshlrev_b32_e32 v36, 16, v59
	v_and_b32_e32 v37, 0xffff0000, v59
	v_pk_mul_f32 v[58:59], v[40:41], v[40:41]
	v_add_f32_e32 v9, v57, v9
	v_add_f32_e32 v9, v58, v9
	v_pk_mul_f32 v[60:61], v[34:35], v[34:35]
	v_add_f32_e32 v9, v59, v9
	v_add_f32_e32 v9, v60, v9
	v_pk_mul_f32 v[68:69], v[36:37], v[36:37]
	v_add_f32_e32 v9, v61, v9
	v_add_f32_e32 v9, v68, v9
	v_add_f32_e32 v9, v69, v9
	ds_bpermute_b32 v31, v3, v9
	s_waitcnt lgkmcnt(0)
	v_add_f32_e32 v9, v9, v31
	ds_bpermute_b32 v31, v7, v9
	s_waitcnt lgkmcnt(0)
	v_add_f32_e32 v9, v9, v31
	ds_bpermute_b32 v31, v51, v9
	s_waitcnt lgkmcnt(0)
	v_add_f32_e32 v9, v9, v31
	ds_bpermute_b32 v31, v52, v9
	s_waitcnt lgkmcnt(0)
	v_add_f32_e32 v9, v9, v31
	ds_bpermute_b32 v31, v53, v9
	s_waitcnt lgkmcnt(0)
	v_add_f32_e32 v9, v9, v31
	ds_bpermute_b32 v31, v54, v9
	s_waitcnt lgkmcnt(0)
	v_add_f32_e32 v9, v9, v31
	v_fmamk_f32 v9, v9, 0x3a800000, v167
	v_mul_f32_e32 v31, 0x4b800000, v9
	v_cmp_gt_f32_e32 vcc, s0, v9
	s_nop 1
	v_cndmask_b32_e32 v9, v9, v31, vcc
	v_rsq_f32_e32 v9, v9
	s_nop 0
	v_mul_f32_e32 v31, 0x45800000, v9
	v_cndmask_b32_e32 v50, v9, v31, vcc
	s_and_saveexec_b64 s[16:17], s[6:7]
	s_cbranch_execz .LBB0_542
	v_lshl_add_u64 v[56:57], v[4:5], 2, s[20:21]
	global_store_dword v[56:57], v50, off

.LBB0_657:
	s_or_b64 exec, exec, s[4:5]
	v_mov_b32_e32 v0, v166
	v_readlane_b32 s0, v243, 18
	v_and_b32_e32 v146, 15, v0
	v_and_b32_e32 v46, 0xffffff00, v0
	v_lshlrev_b32_e32 v47, 2, v146
	v_add3_u32 v48, s0, v46, v47
	v_and_b32_e32 v41, 63, v0
	v_lshlrev_b32_e32 v39, 2, v41
	v_xor_b32_e32 v40, 64, v39
	v_xor_b32_e32 v39, 0x80, v39
	v_bfe_u32 v38, v0, 6, 2
	v_cmp_gt_u32_e32 vcc, 16, v41
	v_lshlrev_b32_e32 v41, 11, v38
	v_add_u32_e32 v41, v48, v41
	v_mul_f32_e32 v170, v135, v135
	v_mul_f32_e32 v171, v127, v127
	v_mul_f32_e32 v172, v119, v119
	v_mul_f32_e32 v173, v111, v111
	v_fmac_f32_e32 v170, v134, v134
	v_fmac_f32_e32 v171, v126, v126
	v_fmac_f32_e32 v172, v118, v118
	v_fmac_f32_e32 v173, v110, v110
	v_fmac_f32_e32 v170, v136, v136
	v_fmac_f32_e32 v171, v128, v128
	v_fmac_f32_e32 v172, v120, v120
	v_fmac_f32_e32 v173, v112, v112
	v_fmac_f32_e32 v170, v137, v137
	v_fmac_f32_e32 v171, v129, v129
	v_fmac_f32_e32 v172, v121, v121
	v_fmac_f32_e32 v173, v113, v113
	v_fmac_f32_e32 v170, v130, v130
	v_fmac_f32_e32 v171, v122, v122
	v_fmac_f32_e32 v172, v114, v114
	v_fmac_f32_e32 v173, v106, v106
	v_fmac_f32_e32 v170, v131, v131
	v_fmac_f32_e32 v171, v123, v123
	v_fmac_f32_e32 v172, v115, v115
	v_fmac_f32_e32 v173, v107, v107
	v_fmac_f32_e32 v170, v132, v132
	v_fmac_f32_e32 v171, v124, v124
	v_fmac_f32_e32 v172, v116, v116
	v_fmac_f32_e32 v173, v108, v108
	v_fmac_f32_e32 v170, v133, v133
	v_fmac_f32_e32 v171, v125, v125
	v_fmac_f32_e32 v172, v117, v117
	v_fmac_f32_e32 v173, v109, v109
	v_mul_f32_e32 v174, v103, v103
	v_mul_f32_e32 v175, v95, v95
	v_mul_f32_e32 v176, v87, v87
	v_mul_f32_e32 v177, v79, v79
	v_fmac_f32_e32 v174, v102, v102
	v_fmac_f32_e32 v175, v94, v94
	v_fmac_f32_e32 v176, v86, v86
	v_fmac_f32_e32 v177, v78, v78
	v_fmac_f32_e32 v174, v104, v104
	v_fmac_f32_e32 v175, v96, v96
	v_fmac_f32_e32 v176, v88, v88
	v_fmac_f32_e32 v177, v80, v80
	v_fmac_f32_e32 v174, v105, v105
	v_fmac_f32_e32 v175, v97, v97
	v_fmac_f32_e32 v176, v89, v89
	v_fmac_f32_e32 v177, v81, v81
	v_fmac_f32_e32 v174, v98, v98
	v_fmac_f32_e32 v175, v90, v90
	v_fmac_f32_e32 v176, v82, v82
	v_fmac_f32_e32 v177, v74, v74
	v_fmac_f32_e32 v174, v99, v99
	v_fmac_f32_e32 v175, v91, v91
	v_fmac_f32_e32 v176, v83, v83
	v_fmac_f32_e32 v177, v75, v75
	v_fmac_f32_e32 v174, v100, v100
	v_fmac_f32_e32 v175, v92, v92
	v_fmac_f32_e32 v176, v84, v84
	v_fmac_f32_e32 v177, v76, v76
	v_fmac_f32_e32 v174, v101, v101
	v_fmac_f32_e32 v175, v93, v93
	v_fmac_f32_e32 v176, v85, v85
	v_fmac_f32_e32 v177, v77, v77
	v_mul_f32_e32 v178, v71, v71
	v_mul_f32_e32 v179, v63, v63
	v_mul_f32_e32 v180, v55, v55
	v_mul_f32_e32 v181, v43, v43
	v_fmac_f32_e32 v178, v70, v70
	v_fmac_f32_e32 v179, v62, v62
	v_fmac_f32_e32 v180, v54, v54
	v_fmac_f32_e32 v181, v42, v42
	v_fmac_f32_e32 v178, v72, v72
	v_fmac_f32_e32 v179, v64, v64
	v_fmac_f32_e32 v180, v56, v56
	v_fmac_f32_e32 v181, v44, v44
	v_fmac_f32_e32 v178, v73, v73
	v_fmac_f32_e32 v179, v65, v65
	v_fmac_f32_e32 v180, v57, v57
	v_fmac_f32_e32 v181, v45, v45
	v_fmac_f32_e32 v178, v66, v66
	v_fmac_f32_e32 v179, v58, v58
	v_fmac_f32_e32 v180, v50, v50
	v_fmac_f32_e32 v181, v34, v34
	v_fmac_f32_e32 v178, v67, v67
	v_fmac_f32_e32 v179, v59, v59
	v_fmac_f32_e32 v180, v51, v51
	v_fmac_f32_e32 v181, v35, v35
	v_fmac_f32_e32 v178, v68, v68
	v_fmac_f32_e32 v179, v60, v60
	v_fmac_f32_e32 v180, v52, v52
	v_fmac_f32_e32 v181, v36, v36
	v_fmac_f32_e32 v178, v69, v69
	v_fmac_f32_e32 v179, v61, v61
	v_fmac_f32_e32 v180, v53, v53
	v_fmac_f32_e32 v181, v37, v37
	v_mul_f32_e32 v182, v31, v31
	v_mul_f32_e32 v183, v23, v23
	v_mul_f32_e32 v184, v15, v15
	v_mul_f32_e32 v185, v7, v7
	v_fmac_f32_e32 v182, v30, v30
	v_fmac_f32_e32 v183, v22, v22
	v_fmac_f32_e32 v184, v14, v14
	v_fmac_f32_e32 v185, v6, v6
	v_fmac_f32_e32 v182, v32, v32
	v_fmac_f32_e32 v183, v24, v24
	v_fmac_f32_e32 v184, v16, v16
	v_fmac_f32_e32 v185, v8, v8
	v_fmac_f32_e32 v182, v33, v33
	v_fmac_f32_e32 v183, v25, v25
	v_fmac_f32_e32 v184, v17, v17
	v_fmac_f32_e32 v185, v9, v9
	v_fmac_f32_e32 v182, v26, v26
	v_fmac_f32_e32 v183, v18, v18
	v_fmac_f32_e32 v184, v10, v10
	v_fmac_f32_e32 v185, v2, v2
	v_fmac_f32_e32 v182, v27, v27
	v_fmac_f32_e32 v183, v19, v19
	v_fmac_f32_e32 v184, v11, v11
	v_fmac_f32_e32 v185, v3, v3
	v_fmac_f32_e32 v182, v28, v28
	v_fmac_f32_e32 v183, v20, v20
	v_fmac_f32_e32 v184, v12, v12
	v_fmac_f32_e32 v185, v4, v4
	v_fmac_f32_e32 v182, v29, v29
	v_fmac_f32_e32 v183, v21, v21
	v_fmac_f32_e32 v184, v13, v13
	v_fmac_f32_e32 v185, v5, v5
	ds_bpermute_b32 v186, v40, v170
	ds_bpermute_b32 v187, v40, v171
	ds_bpermute_b32 v188, v40, v172
	ds_bpermute_b32 v189, v40, v173
	ds_bpermute_b32 v190, v40, v174
	ds_bpermute_b32 v191, v40, v175
	ds_bpermute_b32 v192, v40, v176
	ds_bpermute_b32 v193, v40, v177
	ds_bpermute_b32 v194, v40, v178
	ds_bpermute_b32 v195, v40, v179
	ds_bpermute_b32 v196, v40, v180
	ds_bpermute_b32 v197, v40, v181
	ds_bpermute_b32 v198, v40, v182
	ds_bpermute_b32 v199, v40, v183
	ds_bpermute_b32 v200, v40, v184
	s_waitcnt lgkmcnt(14)
	ds_bpermute_b32 v201, v40, v185
	s_waitcnt lgkmcnt(0)
	v_add_f32_e32 v170, v170, v186
	v_add_f32_e32 v171, v171, v187
	v_add_f32_e32 v172, v172, v188
	v_add_f32_e32 v173, v173, v189
	v_add_f32_e32 v174, v174, v190
	v_add_f32_e32 v175, v175, v191
	v_add_f32_e32 v176, v176, v192
	v_add_f32_e32 v177, v177, v193
	v_add_f32_e32 v178, v178, v194
	v_add_f32_e32 v179, v179, v195
	v_add_f32_e32 v180, v180, v196
	v_add_f32_e32 v181, v181, v197
	v_add_f32_e32 v182, v182, v198
	v_add_f32_e32 v183, v183, v199
	v_add_f32_e32 v184, v184, v200
	v_add_f32_e32 v185, v185, v201
	ds_bpermute_b32 v186, v39, v170
	ds_bpermute_b32 v187, v39, v171
	ds_bpermute_b32 v188, v39, v172
	ds_bpermute_b32 v189, v39, v173
	ds_bpermute_b32 v190, v39, v174
	ds_bpermute_b32 v191, v39, v175
	ds_bpermute_b32 v192, v39, v176
	ds_bpermute_b32 v193, v39, v177
	ds_bpermute_b32 v194, v39, v178
	ds_bpermute_b32 v195, v39, v179
	ds_bpermute_b32 v196, v39, v180
	ds_bpermute_b32 v197, v39, v181
	ds_bpermute_b32 v198, v39, v182
	ds_bpermute_b32 v199, v39, v183
	ds_bpermute_b32 v200, v39, v184
	s_waitcnt lgkmcnt(14)
	ds_bpermute_b32 v201, v39, v185
	s_waitcnt lgkmcnt(0)
	s_and_saveexec_b64 s[4:5], vcc
	v_add_f32_e32 v170, v170, v186
	ds_write_b32 v41, v170
	v_add_f32_e32 v171, v171, v187
	ds_write_b32 v41, v171 offset:64
	v_add_f32_e32 v172, v172, v188
	ds_write_b32 v41, v172 offset:128
	v_add_f32_e32 v173, v173, v189
	ds_write_b32 v41, v173 offset:192
	v_add_f32_e32 v174, v174, v190
	ds_write_b32 v41, v174 offset:512
	v_add_f32_e32 v175, v175, v191
	ds_write_b32 v41, v175 offset:576
	v_add_f32_e32 v176, v176, v192
	ds_write_b32 v41, v176 offset:640
	v_add_f32_e32 v177, v177, v193
	ds_write_b32 v41, v177 offset:704
	v_add_f32_e32 v178, v178, v194
	ds_write_b32 v41, v178 offset:1024
	v_add_f32_e32 v179, v179, v195
	ds_write_b32 v41, v179 offset:1088
	v_add_f32_e32 v180, v180, v196
	ds_write_b32 v41, v180 offset:1152
	v_add_f32_e32 v181, v181, v197
	ds_write_b32 v41, v181 offset:1216
	v_add_f32_e32 v182, v182, v198
	ds_write_b32 v41, v182 offset:1536
	v_add_f32_e32 v183, v183, v199
	ds_write_b32 v41, v183 offset:1600
	v_add_f32_e32 v184, v184, v200
	ds_write_b32 v41, v184 offset:1664
	v_add_f32_e32 v185, v185, v201
	ds_write_b32 v41, v185 offset:1728
	s_or_b64 exec, exec, s[4:5]
	s_waitcnt lgkmcnt(0)
	v_lshrrev_b32_e32 v39, 1, v0
	v_and_b32_e32 v39, 24, v39
	v_lshl_or_b32 v149, v38, 5, v39
	v_lshlrev_b32_e32 v46, 2, v149
	s_waitcnt vmcnt(0)
	s_barrier
	global_load_dwordx4 v[38:41], v46, s[18:19] offset:16
	s_nop 0
	global_load_dwordx4 v[46:49], v46, s[18:19]
	v_ashrrev_i32_e32 v0, 2, v0
	s_movk_i32 s0, 0xffc0
	v_and_or_b32 v148, v0, s0, v146
	v_lshl_add_u32 v0, v148, 2, 0
	v_add_u32_e32 v147, 0x20000, v0
	ds_read2st64_b32 v[144:145], v147 offset1:8
	ds_read2st64_b32 v[142:143], v147 offset0:16 offset1:24
	v_add_u32_e32 v138, s9, v148
	s_cmp_lt_i32 s8, 1
	s_mov_b64 s[4:5], -1
	s_cbranch_scc1 .LBB0_695
	s_cmp_lg_u32 s8, 1
	s_cbranch_scc0 .LBB0_692
	v_ashrrev_i32_e32 v0, 4, v138
	s_movk_i32 s0, 0x1040
	v_mad_i64_i32 v[140:141], s[0:1], v0, s0, 0
	v_or_b32_e32 v140, v140, v146
	s_mov_b64 s[0:1], 0x1000
	v_lshl_add_u64 v[140:141], v[140:141], 0, s[0:1]
	s_mov_b64 s[4:5], 0
